# dropped the invalidates in the scan acquire and last-layer panel acquire (no plain loads of foreign data follow)
# speedup vs baseline: 1.0566x; 1.0020x over previous
.LBB0_593:
	v_readlane_b32 s2, v253, 44
	v_readlane_b32 s3, v253, 45
	s_andn2_b64 vcc, exec, s[2:3]
	s_mov_b32 s4, 0x10000
	s_mov_b32 s9, 0x14000
	s_mov_b32 s26, 0xc000
	s_mov_b32 s27, 0x20000
	s_mov_b32 s28, 0x24000
	s_mov_b32 s29, 0x28000
	s_mov_b32 s30, 0x2c000
	s_mov_b32 s31, 0x30000
	s_mov_b32 s34, 0x34000
	s_load_dwordx2 s[10:11], s[0:1], 0x60
	s_waitcnt lgkmcnt(0)
	s_load_dwordx2 s[18:19], s[0:1], 0x68
	s_waitcnt lgkmcnt(0)
	s_mov_b32 s35, 0x38000
	s_mov_b32 s36, 0x3c000
	s_add_u32 s10, s18, 0x1600000
	s_addc_u32 s11, s19, 0
	s_add_u32 s12, s18, 0x1800000
	s_addc_u32 s13, s19, 0
	s_add_u32 s14, s18, 0xe800000
	s_addc_u32 s15, s19, 0
	s_lshl_b32 s80, s16, 6
	s_lshl_b64 s[18:19], s[80:81], 2
	s_getpc_b64 s[20:21]
	s_add_u32 s20, s20, g_ctl@rel32@lo+14340
	s_addc_u32 s21, s21, g_ctl@rel32@hi+14348
	s_add_u32 s18, s20, s18
	v_readlane_b32 s2, v252, 9
	s_addc_u32 s19, s21, s19
	s_mov_b32 s20, s2
	v_readlane_b32 s3, v252, 10
	s_branch .LBB0_597
.LBB0_595:
	s_waitcnt vmcnt(0)
.LBB0_596:
	s_or_b64 exec, exec, s[22:23]
	s_barrier
	v_readfirstlane_b32 s3, v0
	s_nop 3
	s_cmp_gt_u32 s3, 0x7f
	s_cbranch_scc1 .LBB0_606
	s_lshr_b32 s24, s20, 4
	s_and_b32 s2, s20, 15
	v_lshrrev_b32_e32 v1, 5, v0
	v_lshl_add_u32 v1, s2, 2, v1
	v_and_b32_e32 v2, 31, v0
	v_lshlrev_b32_e32 v2, 1, v2
	v_lshl_add_u32 v3, v1, 6, v2
	v_lshlrev_b32_e32 v4, 2, v3
	v_lshlrev_b32_e32 v5, 2, v2
	v_lshlrev_b32_e32 v3, 1, v3
	s_lshl_b32 s3, s24, 19
	s_add_u32 s22, s12, s3
	s_addc_u32 s23, s13, 0
	s_lshl_b32 s3, s24, 13
	s_add_u32 s18, s10, s3
	s_addc_u32 s19, s11, 0
	s_lshl_b32 s3, s24, 18
	s_add_u32 s24, s14, s3
	s_addc_u32 s25, s15, 0
	v_mov_b32_e32 v6, 0
	v_mov_b32_e32 v7, 0
	global_load_dwordx2 v[10:11], v4, s[22:23] nt
	global_load_dwordx2 v[80:81], v5, s[18:19] offset:0
	s_add_u32 s22, s22, 0x4000
	s_addc_u32 s23, s23, 0
	global_load_dwordx2 v[12:13], v4, s[22:23] nt
	global_load_dwordx2 v[82:83], v5, s[18:19] offset:256
	s_add_u32 s22, s22, 0x4000
	s_addc_u32 s23, s23, 0
	global_load_dwordx2 v[14:15], v4, s[22:23] nt
	global_load_dwordx2 v[84:85], v5, s[18:19] offset:512
	s_add_u32 s22, s22, 0x4000
	s_addc_u32 s23, s23, 0
	global_load_dwordx2 v[16:17], v4, s[22:23] nt
	global_load_dwordx2 v[86:87], v5, s[18:19] offset:768
	s_add_u32 s22, s22, 0x4000
	s_addc_u32 s23, s23, 0
	global_load_dwordx2 v[18:19], v4, s[22:23] nt
	global_load_dwordx2 v[88:89], v5, s[18:19] offset:1024
	s_add_u32 s22, s22, 0x4000
	s_addc_u32 s23, s23, 0
	global_load_dwordx2 v[20:21], v4, s[22:23] nt
	global_load_dwordx2 v[90:91], v5, s[18:19] offset:1280
	s_add_u32 s22, s22, 0x4000
	s_addc_u32 s23, s23, 0
	global_load_dwordx2 v[22:23], v4, s[22:23] nt
	global_load_dwordx2 v[92:93], v5, s[18:19] offset:1536
	s_add_u32 s22, s22, 0x4000
	s_addc_u32 s23, s23, 0
	global_load_dwordx2 v[24:25], v4, s[22:23] nt
	global_load_dwordx2 v[94:95], v5, s[18:19] offset:1792
	s_add_u32 s22, s22, 0x4000
	s_addc_u32 s23, s23, 0
	global_load_dwordx2 v[26:27], v4, s[22:23] nt
	global_load_dwordx2 v[96:97], v5, s[18:19] offset:2048
	s_add_u32 s22, s22, 0x4000
	s_addc_u32 s23, s23, 0
	global_load_dwordx2 v[28:29], v4, s[22:23] nt
	global_load_dwordx2 v[98:99], v5, s[18:19] offset:2304
	s_add_u32 s22, s22, 0x4000
	s_addc_u32 s23, s23, 0
	global_load_dwordx2 v[30:31], v4, s[22:23] nt
	global_load_dwordx2 v[100:101], v5, s[18:19] offset:2560
	s_add_u32 s22, s22, 0x4000
	s_addc_u32 s23, s23, 0
	global_load_dwordx2 v[32:33], v4, s[22:23] nt
	global_load_dwordx2 v[102:103], v5, s[18:19] offset:2816
	s_add_u32 s22, s22, 0x4000
	s_addc_u32 s23, s23, 0
	global_load_dwordx2 v[34:35], v4, s[22:23] nt
	global_load_dwordx2 v[104:105], v5, s[18:19] offset:3072
	s_add_u32 s22, s22, 0x4000
	s_addc_u32 s23, s23, 0
	global_load_dwordx2 v[36:37], v4, s[22:23] nt
	global_load_dwordx2 v[106:107], v5, s[18:19] offset:3328
	s_add_u32 s22, s22, 0x4000
	s_addc_u32 s23, s23, 0
	global_load_dwordx2 v[38:39], v4, s[22:23] nt
	global_load_dwordx2 v[108:109], v5, s[18:19] offset:3584
	s_add_u32 s22, s22, 0x4000
	s_addc_u32 s23, s23, 0
	global_load_dwordx2 v[40:41], v4, s[22:23] nt
	global_load_dwordx2 v[110:111], v5, s[18:19] offset:3840
	s_add_u32 s22, s22, 0x4000
	s_addc_u32 s23, s23, 0
	s_add_u32 s18, s18, 0x1000
	s_addc_u32 s19, s19, 0
	global_load_dwordx2 v[42:43], v4, s[22:23] nt
	global_load_dwordx2 v[112:113], v5, s[18:19] offset:0
	s_add_u32 s22, s22, 0x4000
	s_addc_u32 s23, s23, 0
	global_load_dwordx2 v[44:45], v4, s[22:23] nt
	global_load_dwordx2 v[114:115], v5, s[18:19] offset:256
	s_add_u32 s22, s22, 0x4000
	s_addc_u32 s23, s23, 0
	global_load_dwordx2 v[46:47], v4, s[22:23] nt
	global_load_dwordx2 v[116:117], v5, s[18:19] offset:512
	s_add_u32 s22, s22, 0x4000
	s_addc_u32 s23, s23, 0
	global_load_dwordx2 v[48:49], v4, s[22:23] nt
	global_load_dwordx2 v[118:119], v5, s[18:19] offset:768
	s_add_u32 s22, s22, 0x4000
	s_addc_u32 s23, s23, 0
	global_load_dwordx2 v[50:51], v4, s[22:23] nt
	global_load_dwordx2 v[120:121], v5, s[18:19] offset:1024
	s_add_u32 s22, s22, 0x4000
	s_addc_u32 s23, s23, 0
	global_load_dwordx2 v[52:53], v4, s[22:23] nt
	global_load_dwordx2 v[122:123], v5, s[18:19] offset:1280
	s_add_u32 s22, s22, 0x4000
	s_addc_u32 s23, s23, 0
	global_load_dwordx2 v[54:55], v4, s[22:23] nt
	global_load_dwordx2 v[124:125], v5, s[18:19] offset:1536
	s_add_u32 s22, s22, 0x4000
	s_addc_u32 s23, s23, 0
	global_load_dwordx2 v[56:57], v4, s[22:23] nt
	global_load_dwordx2 v[126:127], v5, s[18:19] offset:1792
	s_add_u32 s22, s22, 0x4000
	s_addc_u32 s23, s23, 0
	global_load_dwordx2 v[58:59], v4, s[22:23] nt
	global_load_dwordx2 v[128:129], v5, s[18:19] offset:2048
	s_add_u32 s22, s22, 0x4000
	s_addc_u32 s23, s23, 0
	global_load_dwordx2 v[60:61], v4, s[22:23] nt
	global_load_dwordx2 v[130:131], v5, s[18:19] offset:2304
	s_add_u32 s22, s22, 0x4000
	s_addc_u32 s23, s23, 0
	global_load_dwordx2 v[62:63], v4, s[22:23] nt
	global_load_dwordx2 v[132:133], v5, s[18:19] offset:2560
	s_add_u32 s22, s22, 0x4000
	s_addc_u32 s23, s23, 0
	global_load_dwordx2 v[64:65], v4, s[22:23] nt
	global_load_dwordx2 v[134:135], v5, s[18:19] offset:2816
	s_add_u32 s22, s22, 0x4000
	s_addc_u32 s23, s23, 0
	global_load_dwordx2 v[66:67], v4, s[22:23] nt
	global_load_dwordx2 v[136:137], v5, s[18:19] offset:3072
	s_add_u32 s22, s22, 0x4000
	s_addc_u32 s23, s23, 0
	global_load_dwordx2 v[68:69], v4, s[22:23] nt
	global_load_dwordx2 v[138:139], v5, s[18:19] offset:3328
	s_add_u32 s22, s22, 0x4000
	s_addc_u32 s23, s23, 0
	global_load_dwordx2 v[70:71], v4, s[22:23] nt
	global_load_dwordx2 v[140:141], v5, s[18:19] offset:3584
	s_add_u32 s22, s22, 0x4000
	s_addc_u32 s23, s23, 0
	global_load_dwordx2 v[72:73], v4, s[22:23] nt
	global_load_dwordx2 v[142:143], v5, s[18:19] offset:3840
	s_add_u32 s22, s22, 0x4000
	s_addc_u32 s23, s23, 0
	s_add_u32 s18, s18, 0x1000
	s_addc_u32 s19, s19, 0
	v_cvt_pk_bf16_f32 v8, v6, v7
	global_store_dword v3, v8, s[24:25]
	s_add_u32 s24, s24, 0x2000
	s_addc_u32 s25, s25, 0
	s_waitcnt vmcnt(63)
	v_fma_f32 v6, v6, v80, v10
	v_fma_f32 v7, v7, v81, v11
	v_cvt_pk_bf16_f32 v8, v6, v7
	global_store_dword v3, v8, s[24:25]
	s_add_u32 s24, s24, 0x2000
	s_addc_u32 s25, s25, 0
	s_waitcnt vmcnt(62)
	v_fma_f32 v6, v6, v82, v12
	v_fma_f32 v7, v7, v83, v13
	v_cvt_pk_bf16_f32 v8, v6, v7
	global_store_dword v3, v8, s[24:25]
	s_add_u32 s24, s24, 0x2000
	s_addc_u32 s25, s25, 0
	s_waitcnt vmcnt(61)
	v_fma_f32 v6, v6, v84, v14
	v_fma_f32 v7, v7, v85, v15
	v_cvt_pk_bf16_f32 v8, v6, v7
	global_store_dword v3, v8, s[24:25]
	s_add_u32 s24, s24, 0x2000
	s_addc_u32 s25, s25, 0
	s_waitcnt vmcnt(60)
	v_fma_f32 v6, v6, v86, v16
	v_fma_f32 v7, v7, v87, v17
	v_cvt_pk_bf16_f32 v8, v6, v7
	global_store_dword v3, v8, s[24:25]
	s_add_u32 s24, s24, 0x2000
	s_addc_u32 s25, s25, 0
	s_waitcnt vmcnt(59)
	v_fma_f32 v6, v6, v88, v18
	v_fma_f32 v7, v7, v89, v19
	v_cvt_pk_bf16_f32 v8, v6, v7
	global_store_dword v3, v8, s[24:25]
	s_add_u32 s24, s24, 0x2000
	s_addc_u32 s25, s25, 0
	s_waitcnt vmcnt(58)
	v_fma_f32 v6, v6, v90, v20
	v_fma_f32 v7, v7, v91, v21
	v_cvt_pk_bf16_f32 v8, v6, v7
	global_store_dword v3, v8, s[24:25]
	s_add_u32 s24, s24, 0x2000
	s_addc_u32 s25, s25, 0
	s_waitcnt vmcnt(57)
	v_fma_f32 v6, v6, v92, v22
	v_fma_f32 v7, v7, v93, v23
	v_cvt_pk_bf16_f32 v8, v6, v7
	global_store_dword v3, v8, s[24:25]
	s_add_u32 s24, s24, 0x2000
	s_addc_u32 s25, s25, 0
	s_waitcnt vmcnt(56)
	v_fma_f32 v6, v6, v94, v24
	v_fma_f32 v7, v7, v95, v25
	v_cvt_pk_bf16_f32 v8, v6, v7
	global_store_dword v3, v8, s[24:25]
	s_add_u32 s24, s24, 0x2000
	s_addc_u32 s25, s25, 0
	s_waitcnt vmcnt(55)
	v_fma_f32 v6, v6, v96, v26
	v_fma_f32 v7, v7, v97, v27
	v_cvt_pk_bf16_f32 v8, v6, v7
	global_store_dword v3, v8, s[24:25]
	s_add_u32 s24, s24, 0x2000
	s_addc_u32 s25, s25, 0
	s_waitcnt vmcnt(54)
	v_fma_f32 v6, v6, v98, v28
	v_fma_f32 v7, v7, v99, v29
	v_cvt_pk_bf16_f32 v8, v6, v7
	global_store_dword v3, v8, s[24:25]
	s_add_u32 s24, s24, 0x2000
	s_addc_u32 s25, s25, 0
	s_waitcnt vmcnt(53)
	v_fma_f32 v6, v6, v100, v30
	v_fma_f32 v7, v7, v101, v31
	v_cvt_pk_bf16_f32 v8, v6, v7
	global_store_dword v3, v8, s[24:25]
	s_add_u32 s24, s24, 0x2000
	s_addc_u32 s25, s25, 0
	s_waitcnt vmcnt(52)
	v_fma_f32 v6, v6, v102, v32
	v_fma_f32 v7, v7, v103, v33
	v_cvt_pk_bf16_f32 v8, v6, v7
	global_store_dword v3, v8, s[24:25]
	s_add_u32 s24, s24, 0x2000
	s_addc_u32 s25, s25, 0
	s_waitcnt vmcnt(51)
	v_fma_f32 v6, v6, v104, v34
	v_fma_f32 v7, v7, v105, v35
	v_cvt_pk_bf16_f32 v8, v6, v7
	global_store_dword v3, v8, s[24:25]
	s_add_u32 s24, s24, 0x2000
	s_addc_u32 s25, s25, 0
	s_waitcnt vmcnt(50)
	v_fma_f32 v6, v6, v106, v36
	v_fma_f32 v7, v7, v107, v37
	v_cvt_pk_bf16_f32 v8, v6, v7
	global_store_dword v3, v8, s[24:25]
	s_add_u32 s24, s24, 0x2000
	s_addc_u32 s25, s25, 0
	s_waitcnt vmcnt(49)
	v_fma_f32 v6, v6, v108, v38
	v_fma_f32 v7, v7, v109, v39
	v_cvt_pk_bf16_f32 v8, v6, v7
	global_store_dword v3, v8, s[24:25]
	s_add_u32 s24, s24, 0x2000
	s_addc_u32 s25, s25, 0
	s_waitcnt vmcnt(48)
	v_fma_f32 v6, v6, v110, v40
	v_fma_f32 v7, v7, v111, v41
	v_cvt_pk_bf16_f32 v8, v6, v7
	global_store_dword v3, v8, s[24:25]
	s_add_u32 s24, s24, 0x2000
	s_addc_u32 s25, s25, 0
	s_waitcnt vmcnt(47)
	v_fma_f32 v6, v6, v112, v42
	v_fma_f32 v7, v7, v113, v43
	v_cvt_pk_bf16_f32 v8, v6, v7
	global_store_dword v3, v8, s[24:25]
	s_add_u32 s24, s24, 0x2000
	s_addc_u32 s25, s25, 0
	s_waitcnt vmcnt(46)
	v_fma_f32 v6, v6, v114, v44
	v_fma_f32 v7, v7, v115, v45
	v_cvt_pk_bf16_f32 v8, v6, v7
	global_store_dword v3, v8, s[24:25]
	s_add_u32 s24, s24, 0x2000
	s_addc_u32 s25, s25, 0
	s_waitcnt vmcnt(45)
	v_fma_f32 v6, v6, v116, v46
	v_fma_f32 v7, v7, v117, v47
	v_cvt_pk_bf16_f32 v8, v6, v7
	global_store_dword v3, v8, s[24:25]
	s_add_u32 s24, s24, 0x2000
	s_addc_u32 s25, s25, 0
	s_waitcnt vmcnt(44)
	v_fma_f32 v6, v6, v118, v48
	v_fma_f32 v7, v7, v119, v49
	v_cvt_pk_bf16_f32 v8, v6, v7
	global_store_dword v3, v8, s[24:25]
	s_add_u32 s24, s24, 0x2000
	s_addc_u32 s25, s25, 0
	s_waitcnt vmcnt(43)
	v_fma_f32 v6, v6, v120, v50
	v_fma_f32 v7, v7, v121, v51
	v_cvt_pk_bf16_f32 v8, v6, v7
	global_store_dword v3, v8, s[24:25]
	s_add_u32 s24, s24, 0x2000
	s_addc_u32 s25, s25, 0
	s_waitcnt vmcnt(42)
	v_fma_f32 v6, v6, v122, v52
	v_fma_f32 v7, v7, v123, v53
	v_cvt_pk_bf16_f32 v8, v6, v7
	global_store_dword v3, v8, s[24:25]
	s_add_u32 s24, s24, 0x2000
	s_addc_u32 s25, s25, 0
	s_waitcnt vmcnt(41)
	v_fma_f32 v6, v6, v124, v54
	v_fma_f32 v7, v7, v125, v55
	v_cvt_pk_bf16_f32 v8, v6, v7
	global_store_dword v3, v8, s[24:25]
	s_add_u32 s24, s24, 0x2000
	s_addc_u32 s25, s25, 0
	s_waitcnt vmcnt(40)
	v_fma_f32 v6, v6, v126, v56
	v_fma_f32 v7, v7, v127, v57
	v_cvt_pk_bf16_f32 v8, v6, v7
	global_store_dword v3, v8, s[24:25]
	s_add_u32 s24, s24, 0x2000
	s_addc_u32 s25, s25, 0
	s_waitcnt vmcnt(39)
	v_fma_f32 v6, v6, v128, v58
	v_fma_f32 v7, v7, v129, v59
	v_cvt_pk_bf16_f32 v8, v6, v7
	global_store_dword v3, v8, s[24:25]
	s_add_u32 s24, s24, 0x2000
	s_addc_u32 s25, s25, 0
	s_waitcnt vmcnt(38)
	v_fma_f32 v6, v6, v130, v60
	v_fma_f32 v7, v7, v131, v61
	v_cvt_pk_bf16_f32 v8, v6, v7
	global_store_dword v3, v8, s[24:25]
	s_add_u32 s24, s24, 0x2000
	s_addc_u32 s25, s25, 0
	s_waitcnt vmcnt(37)
	v_fma_f32 v6, v6, v132, v62
	v_fma_f32 v7, v7, v133, v63
	v_cvt_pk_bf16_f32 v8, v6, v7
	global_store_dword v3, v8, s[24:25]
	s_add_u32 s24, s24, 0x2000
	s_addc_u32 s25, s25, 0
	s_waitcnt vmcnt(36)
	v_fma_f32 v6, v6, v134, v64
	v_fma_f32 v7, v7, v135, v65
	v_cvt_pk_bf16_f32 v8, v6, v7
	global_store_dword v3, v8, s[24:25]
	s_add_u32 s24, s24, 0x2000
	s_addc_u32 s25, s25, 0
	s_waitcnt vmcnt(35)
	v_fma_f32 v6, v6, v136, v66
	v_fma_f32 v7, v7, v137, v67
	v_cvt_pk_bf16_f32 v8, v6, v7
	global_store_dword v3, v8, s[24:25]
	s_add_u32 s24, s24, 0x2000
	s_addc_u32 s25, s25, 0
	s_waitcnt vmcnt(34)
	v_fma_f32 v6, v6, v138, v68
	v_fma_f32 v7, v7, v139, v69
	v_cvt_pk_bf16_f32 v8, v6, v7
	global_store_dword v3, v8, s[24:25]
	s_add_u32 s24, s24, 0x2000
	s_addc_u32 s25, s25, 0
	s_waitcnt vmcnt(33)
	v_fma_f32 v6, v6, v140, v70
	v_fma_f32 v7, v7, v141, v71
	v_cvt_pk_bf16_f32 v8, v6, v7
	global_store_dword v3, v8, s[24:25]
	s_add_u32 s24, s24, 0x2000
	s_addc_u32 s25, s25, 0
	s_waitcnt vmcnt(32)
	v_fma_f32 v6, v6, v142, v72
	v_fma_f32 v7, v7, v143, v73
	s_branch .LBB0_606

.LBB0_811:
	global_load_dword v152, v191, s[36:37] sc1
	s_mov_b64 s[42:43], -1
	s_waitcnt vmcnt(0)
	v_cmp_lt_u32_e32 vcc, 3, v152
	s_cbranch_vccnz .LBB0_810
	s_sleep 1
	global_load_dword v152, v191, s[36:37] sc1
	s_waitcnt vmcnt(0)
	v_cmp_gt_u32_e32 vcc, 4, v152
	s_cbranch_vccz .LBB0_810
	s_sleep 1
	global_load_dword v152, v191, s[36:37] sc1
	s_waitcnt vmcnt(0)
	v_cmp_gt_u32_e32 vcc, 4, v152
	s_cbranch_vccz .LBB0_810
	s_sleep 1
	global_load_dword v152, v191, s[36:37] sc1
	s_waitcnt vmcnt(0)
	v_cmp_gt_u32_e32 vcc, 4, v152
	s_cbranch_vccz .LBB0_810
	s_sleep 1
	global_load_dword v152, v191, s[36:37] sc1
	s_waitcnt vmcnt(0)
	v_cmp_gt_u32_e32 vcc, 4, v152
	s_cbranch_vccz .LBB0_810
	s_add_i32 s20, s20, -5
	s_cmp_eq_u32 s20, 0
	s_cselect_b64 s[42:43], -1, 0
	s_sleep 1
	s_branch .LBB0_810
.LBB0_817:
	s_waitcnt vmcnt(0)
.LBB0_818:
	s_or_b64 exec, exec, s[34:35]
	s_barrier
	global_load_dword v152, v[112:113], off sc1
	v_lshl_add_u64 v[140:141], v[140:141], 2, s[18:19]
	global_load_dwordx4 v[172:175], v[140:141], off
	global_load_dwordx4 v[176:179], v[140:141], off offset:16
	s_mov_b64 s[34:35], -1
	s_waitcnt vmcnt(2)
	v_fmamk_f32 v152, v152, 0x3a800000, v192
	v_mul_f32_e32 v153, 0x4b800000, v152
	v_cmp_gt_f32_e32 vcc, s93, v152
	s_nop 1
	v_cndmask_b32_e32 v152, v152, v153, vcc
	v_rsq_f32_e32 v152, v152
	s_nop 0
	v_mul_f32_e32 v153, 0x45800000, v152
	v_cndmask_b32_e32 v152, v152, v153, vcc
	v_pk_mul_f32 v[124:125], v[124:125], v[152:153] op_sel_hi:[1,0]
	v_pk_mul_f32 v[126:127], v[126:127], v[152:153] op_sel_hi:[1,0]
	v_pk_mul_f32 v[166:167], v[120:121], v[152:153] op_sel_hi:[1,0]
	v_pk_mul_f32 v[180:181], v[122:123], v[152:153] op_sel_hi:[1,0]
	s_waitcnt vmcnt(1)
	v_pk_mul_f32 v[122:123], v[174:175], v[126:127]
	v_pk_mul_f32 v[120:121], v[172:173], v[124:125]
	s_waitcnt vmcnt(0)
	v_pk_mul_f32 v[126:127], v[178:179], v[180:181]
	v_pk_mul_f32 v[124:125], v[176:177], v[166:167]
	global_store_dwordx4 v[138:139], v[120:123], off
	global_store_dwordx4 v[138:139], v[124:127], off offset:16
	global_load_dwordx4 v[120:123], v[140:141], off offset:512
	s_nop 0
	global_load_dwordx4 v[124:127], v[140:141], off offset:528
	v_pk_mul_f32 v[142:143], v[142:143], v[152:153] op_sel_hi:[1,0]
	v_pk_mul_f32 v[144:145], v[144:145], v[152:153] op_sel_hi:[1,0]
	v_pk_mul_f32 v[166:167], v[116:117], v[152:153] op_sel_hi:[1,0]
	v_pk_mul_f32 v[152:153], v[118:119], v[152:153] op_sel_hi:[1,0]
	s_waitcnt vmcnt(1)
	v_pk_mul_f32 v[116:117], v[120:121], v[144:145]
	v_pk_mul_f32 v[118:119], v[122:123], v[142:143]
	s_waitcnt vmcnt(0)
	v_pk_mul_f32 v[120:121], v[124:125], v[152:153]
	v_pk_mul_f32 v[122:123], v[126:127], v[166:167]
	global_store_dwordx4 v[138:139], v[116:119], off offset:512
	global_store_dwordx4 v[138:139], v[120:123], off offset:528
	global_load_dword v124, v[148:149], off sc1
	s_nop 0
	global_load_dwordx4 v[116:119], v[140:141], off
	global_load_dwordx4 v[120:123], v[140:141], off offset:16
	s_waitcnt vmcnt(2)
	v_fmamk_f32 v124, v124, 0x3a800000, v192
	v_mul_f32_e32 v125, 0x4b800000, v124
	v_cmp_gt_f32_e32 vcc, s93, v124
	s_nop 1
	v_cndmask_b32_e32 v124, v124, v125, vcc
	v_rsq_f32_e32 v124, v124
	s_nop 0
	v_mul_f32_e32 v125, 0x45800000, v124
	v_cndmask_b32_e32 v124, v124, v125, vcc
	v_pk_mul_f32 v[108:109], v[108:109], v[124:125] op_sel_hi:[1,0]
	v_pk_mul_f32 v[110:111], v[110:111], v[124:125] op_sel_hi:[1,0]
	v_pk_mul_f32 v[126:127], v[104:105], v[124:125] op_sel_hi:[1,0]
	v_pk_mul_f32 v[138:139], v[106:107], v[124:125] op_sel_hi:[1,0]
	s_waitcnt vmcnt(1)
	v_pk_mul_f32 v[106:107], v[118:119], v[110:111]
	v_pk_mul_f32 v[104:105], v[116:117], v[108:109]
	s_waitcnt vmcnt(0)
	v_pk_mul_f32 v[110:111], v[122:123], v[138:139]
	v_pk_mul_f32 v[108:109], v[120:121], v[126:127]
	global_store_dwordx4 v[114:115], v[104:107], off
	global_store_dwordx4 v[114:115], v[108:111], off offset:16
	global_load_dwordx4 v[104:107], v[140:141], off offset:512
	s_nop 0
	global_load_dwordx4 v[108:111], v[140:141], off offset:528
	v_pk_mul_f32 v[102:103], v[102:103], v[124:125] op_sel_hi:[1,0]
	v_pk_mul_f32 v[116:117], v[146:147], v[124:125] op_sel_hi:[1,0]
	v_pk_mul_f32 v[118:119], v[98:99], v[124:125] op_sel_hi:[1,0]
	v_pk_mul_f32 v[120:121], v[100:101], v[124:125] op_sel_hi:[1,0]
	s_waitcnt vmcnt(1)
	v_pk_mul_f32 v[98:99], v[104:105], v[116:117]
	v_pk_mul_f32 v[100:101], v[106:107], v[102:103]
	s_waitcnt vmcnt(0)
	v_pk_mul_f32 v[102:103], v[108:109], v[120:121]
	v_pk_mul_f32 v[104:105], v[110:111], v[118:119]
	global_store_dwordx4 v[114:115], v[98:101], off offset:512
	global_store_dwordx4 v[114:115], v[102:105], off offset:528
	global_load_dword v106, v[154:155], off sc1
	s_nop 0
	global_load_dwordx4 v[98:101], v[140:141], off
	global_load_dwordx4 v[102:105], v[140:141], off offset:16
	s_waitcnt vmcnt(2)
	v_fmamk_f32 v106, v106, 0x3a800000, v192
	v_mul_f32_e32 v107, 0x4b800000, v106
	v_cmp_gt_f32_e32 vcc, s93, v106
	s_nop 1
	v_cndmask_b32_e32 v106, v106, v107, vcc
	v_rsq_f32_e32 v106, v106
	s_nop 0
	v_mul_f32_e32 v107, 0x45800000, v106
	v_cndmask_b32_e32 v106, v106, v107, vcc
	v_pk_mul_f32 v[92:93], v[92:93], v[106:107] op_sel_hi:[1,0]
	v_pk_mul_f32 v[94:95], v[94:95], v[106:107] op_sel_hi:[1,0]
	v_pk_mul_f32 v[108:109], v[88:89], v[106:107] op_sel_hi:[1,0]
	v_pk_mul_f32 v[110:111], v[90:91], v[106:107] op_sel_hi:[1,0]
	s_waitcnt vmcnt(1)
	v_pk_mul_f32 v[90:91], v[100:101], v[94:95]
	v_pk_mul_f32 v[88:89], v[98:99], v[92:93]
	s_waitcnt vmcnt(0)
	v_pk_mul_f32 v[94:95], v[104:105], v[110:111]
	v_pk_mul_f32 v[92:93], v[102:103], v[108:109]
	global_store_dwordx4 v[96:97], v[88:91], off
	global_store_dwordx4 v[96:97], v[92:95], off offset:16
	global_load_dwordx4 v[88:91], v[140:141], off offset:512
	s_nop 0
	global_load_dwordx4 v[92:95], v[140:141], off offset:528
	v_pk_mul_f32 v[86:87], v[86:87], v[106:107] op_sel_hi:[1,0]
	v_pk_mul_f32 v[98:99], v[150:151], v[106:107] op_sel_hi:[1,0]
	v_pk_mul_f32 v[100:101], v[82:83], v[106:107] op_sel_hi:[1,0]
	v_pk_mul_f32 v[102:103], v[84:85], v[106:107] op_sel_hi:[1,0]
	s_waitcnt vmcnt(1)
	v_pk_mul_f32 v[82:83], v[88:89], v[98:99]
	v_pk_mul_f32 v[84:85], v[90:91], v[86:87]
	s_waitcnt vmcnt(0)
	v_pk_mul_f32 v[86:87], v[92:93], v[102:103]
	v_pk_mul_f32 v[88:89], v[94:95], v[100:101]
	global_store_dwordx4 v[96:97], v[82:85], off offset:512
	global_store_dwordx4 v[96:97], v[86:89], off offset:528
	global_load_dword v90, v[158:159], off sc1
	s_nop 0
	global_load_dwordx4 v[82:85], v[140:141], off
	global_load_dwordx4 v[86:89], v[140:141], off offset:16
	s_waitcnt vmcnt(2)
	v_fmamk_f32 v90, v90, 0x3a800000, v192
	v_mul_f32_e32 v91, 0x4b800000, v90
	v_cmp_gt_f32_e32 vcc, s93, v90
	s_nop 1
	v_cndmask_b32_e32 v90, v90, v91, vcc
	v_rsq_f32_e32 v90, v90
	s_nop 0
	v_mul_f32_e32 v91, 0x45800000, v90
	v_cndmask_b32_e32 v90, v90, v91, vcc
	v_pk_mul_f32 v[76:77], v[76:77], v[90:91] op_sel_hi:[1,0]
	v_pk_mul_f32 v[78:79], v[78:79], v[90:91] op_sel_hi:[1,0]
	v_pk_mul_f32 v[92:93], v[72:73], v[90:91] op_sel_hi:[1,0]
	v_pk_mul_f32 v[94:95], v[74:75], v[90:91] op_sel_hi:[1,0]
	s_waitcnt vmcnt(1)
	v_pk_mul_f32 v[74:75], v[84:85], v[78:79]
	v_pk_mul_f32 v[72:73], v[82:83], v[76:77]
	s_waitcnt vmcnt(0)
	v_pk_mul_f32 v[78:79], v[88:89], v[94:95]
	v_pk_mul_f32 v[76:77], v[86:87], v[92:93]
	global_store_dwordx4 v[80:81], v[72:75], off
	global_store_dwordx4 v[80:81], v[76:79], off offset:16
	global_load_dwordx4 v[72:75], v[140:141], off offset:512
	s_nop 0
	global_load_dwordx4 v[76:79], v[140:141], off offset:528
	v_pk_mul_f32 v[70:71], v[70:71], v[90:91] op_sel_hi:[1,0]
	v_pk_mul_f32 v[82:83], v[156:157], v[90:91] op_sel_hi:[1,0]
	v_pk_mul_f32 v[84:85], v[66:67], v[90:91] op_sel_hi:[1,0]
	v_pk_mul_f32 v[86:87], v[68:69], v[90:91] op_sel_hi:[1,0]
	s_waitcnt vmcnt(1)
	v_pk_mul_f32 v[66:67], v[72:73], v[82:83]
	v_pk_mul_f32 v[68:69], v[74:75], v[70:71]
	s_waitcnt vmcnt(0)
	v_pk_mul_f32 v[70:71], v[76:77], v[86:87]
	v_pk_mul_f32 v[72:73], v[78:79], v[84:85]
	global_store_dwordx4 v[80:81], v[66:69], off offset:512
	global_store_dwordx4 v[80:81], v[70:73], off offset:528
	global_load_dword v74, v[112:113], off offset:512 sc1
	s_nop 0
	global_load_dwordx4 v[66:69], v[140:141], off
	global_load_dwordx4 v[70:73], v[140:141], off offset:16
	s_waitcnt vmcnt(2)
	v_fmamk_f32 v74, v74, 0x3a800000, v192
	v_mul_f32_e32 v75, 0x4b800000, v74
	v_cmp_gt_f32_e32 vcc, s93, v74
	s_nop 1
	v_cndmask_b32_e32 v74, v74, v75, vcc
	v_rsq_f32_e32 v74, v74
	s_nop 0
	v_mul_f32_e32 v75, 0x45800000, v74
	v_cndmask_b32_e32 v74, v74, v75, vcc
	v_pk_mul_f32 v[60:61], v[60:61], v[74:75] op_sel_hi:[1,0]
	v_pk_mul_f32 v[62:63], v[62:63], v[74:75] op_sel_hi:[1,0]
	v_pk_mul_f32 v[76:77], v[56:57], v[74:75] op_sel_hi:[1,0]
	v_pk_mul_f32 v[78:79], v[58:59], v[74:75] op_sel_hi:[1,0]
	s_waitcnt vmcnt(1)
	v_pk_mul_f32 v[58:59], v[68:69], v[62:63]
	v_pk_mul_f32 v[56:57], v[66:67], v[60:61]
	s_waitcnt vmcnt(0)
	v_pk_mul_f32 v[62:63], v[72:73], v[78:79]
	v_pk_mul_f32 v[60:61], v[70:71], v[76:77]
	global_store_dwordx4 v[64:65], v[56:59], off
	global_store_dwordx4 v[64:65], v[60:63], off offset:16
	global_load_dwordx4 v[56:59], v[140:141], off offset:512
	s_nop 0
	global_load_dwordx4 v[60:63], v[140:141], off offset:528
	v_pk_mul_f32 v[54:55], v[54:55], v[74:75] op_sel_hi:[1,0]
	v_pk_mul_f32 v[66:67], v[160:161], v[74:75] op_sel_hi:[1,0]
	v_pk_mul_f32 v[68:69], v[50:51], v[74:75] op_sel_hi:[1,0]
	v_pk_mul_f32 v[70:71], v[52:53], v[74:75] op_sel_hi:[1,0]
	s_waitcnt vmcnt(1)
	v_pk_mul_f32 v[50:51], v[56:57], v[66:67]
	v_pk_mul_f32 v[52:53], v[58:59], v[54:55]
	s_waitcnt vmcnt(0)
	v_pk_mul_f32 v[54:55], v[60:61], v[70:71]
	v_pk_mul_f32 v[56:57], v[62:63], v[68:69]
	global_store_dwordx4 v[64:65], v[50:53], off offset:512
	global_store_dwordx4 v[64:65], v[54:57], off offset:528
	global_load_dword v58, v[112:113], off offset:576 sc1
	s_nop 0
	global_load_dwordx4 v[50:53], v[140:141], off
	global_load_dwordx4 v[54:57], v[140:141], off offset:16
	s_waitcnt vmcnt(2)
	v_fmamk_f32 v58, v58, 0x3a800000, v192
	v_mul_f32_e32 v59, 0x4b800000, v58
	v_cmp_gt_f32_e32 vcc, s93, v58
	s_nop 1
	v_cndmask_b32_e32 v58, v58, v59, vcc
	v_rsq_f32_e32 v58, v58
	s_nop 0
	v_mul_f32_e32 v59, 0x45800000, v58
	v_cndmask_b32_e32 v58, v58, v59, vcc
	v_pk_mul_f32 v[44:45], v[44:45], v[58:59] op_sel_hi:[1,0]
	v_pk_mul_f32 v[46:47], v[46:47], v[58:59] op_sel_hi:[1,0]
	v_pk_mul_f32 v[60:61], v[40:41], v[58:59] op_sel_hi:[1,0]
	v_pk_mul_f32 v[62:63], v[42:43], v[58:59] op_sel_hi:[1,0]
	s_waitcnt vmcnt(1)
	v_pk_mul_f32 v[42:43], v[52:53], v[46:47]
	v_pk_mul_f32 v[40:41], v[50:51], v[44:45]
	s_waitcnt vmcnt(0)
	v_pk_mul_f32 v[46:47], v[56:57], v[62:63]
	v_pk_mul_f32 v[44:45], v[54:55], v[60:61]
	global_store_dwordx4 v[48:49], v[40:43], off
	global_store_dwordx4 v[48:49], v[44:47], off offset:16
	global_load_dwordx4 v[40:43], v[140:141], off offset:512
	s_nop 0
	global_load_dwordx4 v[44:47], v[140:141], off offset:528
	v_pk_mul_f32 v[38:39], v[38:39], v[58:59] op_sel_hi:[1,0]
	v_pk_mul_f32 v[50:51], v[162:163], v[58:59] op_sel_hi:[1,0]
	v_pk_mul_f32 v[52:53], v[34:35], v[58:59] op_sel_hi:[1,0]
	v_pk_mul_f32 v[54:55], v[36:37], v[58:59] op_sel_hi:[1,0]
	s_waitcnt vmcnt(1)
	v_pk_mul_f32 v[34:35], v[40:41], v[50:51]
	v_pk_mul_f32 v[36:37], v[42:43], v[38:39]
	s_waitcnt vmcnt(0)
	v_pk_mul_f32 v[38:39], v[44:45], v[54:55]
	v_pk_mul_f32 v[40:41], v[46:47], v[52:53]
	global_store_dwordx4 v[48:49], v[34:37], off offset:512
	global_store_dwordx4 v[48:49], v[38:41], off offset:528
	global_load_dword v42, v[112:113], off offset:640 sc1
	s_nop 0
	global_load_dwordx4 v[34:37], v[140:141], off
	global_load_dwordx4 v[38:41], v[140:141], off offset:16
	s_waitcnt vmcnt(2)
	v_fmamk_f32 v42, v42, 0x3a800000, v192
	v_mul_f32_e32 v43, 0x4b800000, v42
	v_cmp_gt_f32_e32 vcc, s93, v42
	s_nop 1
	v_cndmask_b32_e32 v42, v42, v43, vcc
	v_rsq_f32_e32 v42, v42
	s_nop 0
	v_mul_f32_e32 v43, 0x45800000, v42
	v_cndmask_b32_e32 v42, v42, v43, vcc
	v_pk_mul_f32 v[28:29], v[28:29], v[42:43] op_sel_hi:[1,0]
	v_pk_mul_f32 v[30:31], v[30:31], v[42:43] op_sel_hi:[1,0]
	v_pk_mul_f32 v[44:45], v[24:25], v[42:43] op_sel_hi:[1,0]
	v_pk_mul_f32 v[46:47], v[26:27], v[42:43] op_sel_hi:[1,0]
	s_waitcnt vmcnt(1)
	v_pk_mul_f32 v[26:27], v[36:37], v[30:31]
	v_pk_mul_f32 v[24:25], v[34:35], v[28:29]
	s_waitcnt vmcnt(0)
	v_pk_mul_f32 v[30:31], v[40:41], v[46:47]
	v_pk_mul_f32 v[28:29], v[38:39], v[44:45]
	global_store_dwordx4 v[32:33], v[24:27], off
	global_store_dwordx4 v[32:33], v[28:31], off offset:16
	global_load_dwordx4 v[24:27], v[140:141], off offset:512
	s_nop 0
	global_load_dwordx4 v[28:31], v[140:141], off offset:528
	v_pk_mul_f32 v[22:23], v[22:23], v[42:43] op_sel_hi:[1,0]
	v_pk_mul_f32 v[34:35], v[164:165], v[42:43] op_sel_hi:[1,0]
	v_pk_mul_f32 v[36:37], v[18:19], v[42:43] op_sel_hi:[1,0]
	v_pk_mul_f32 v[38:39], v[20:21], v[42:43] op_sel_hi:[1,0]
	s_waitcnt vmcnt(1)
	v_pk_mul_f32 v[18:19], v[24:25], v[34:35]
	v_pk_mul_f32 v[20:21], v[26:27], v[22:23]
	s_waitcnt vmcnt(0)
	v_pk_mul_f32 v[22:23], v[28:29], v[38:39]
	v_pk_mul_f32 v[24:25], v[30:31], v[36:37]
	global_store_dwordx4 v[32:33], v[18:21], off offset:512
	global_store_dwordx4 v[32:33], v[22:25], off offset:528
	global_load_dword v26, v[112:113], off offset:704 sc1
	s_nop 0
	global_load_dwordx4 v[18:21], v[140:141], off
	global_load_dwordx4 v[22:25], v[140:141], off offset:16
	s_waitcnt vmcnt(2)
	v_fmamk_f32 v26, v26, 0x3a800000, v192
	v_mul_f32_e32 v27, 0x4b800000, v26
	v_cmp_gt_f32_e32 vcc, s93, v26
	s_nop 1
	v_cndmask_b32_e32 v26, v26, v27, vcc
	v_rsq_f32_e32 v26, v26
	s_nop 0
	v_mul_f32_e32 v27, 0x45800000, v26
	v_cndmask_b32_e32 v26, v26, v27, vcc
	v_pk_mul_f32 v[12:13], v[12:13], v[26:27] op_sel_hi:[1,0]
	v_pk_mul_f32 v[14:15], v[14:15], v[26:27] op_sel_hi:[1,0]
	v_pk_mul_f32 v[28:29], v[8:9], v[26:27] op_sel_hi:[1,0]
	v_pk_mul_f32 v[30:31], v[10:11], v[26:27] op_sel_hi:[1,0]
	s_waitcnt vmcnt(1)
	v_pk_mul_f32 v[10:11], v[20:21], v[14:15]
	v_pk_mul_f32 v[8:9], v[18:19], v[12:13]
	s_waitcnt vmcnt(0)
	v_pk_mul_f32 v[14:15], v[24:25], v[30:31]
	v_pk_mul_f32 v[12:13], v[22:23], v[28:29]
	global_store_dwordx4 v[16:17], v[8:11], off
	global_store_dwordx4 v[16:17], v[12:15], off offset:16
	global_load_dwordx4 v[8:11], v[140:141], off offset:512
	s_nop 0
	global_load_dwordx4 v[12:15], v[140:141], off offset:528
	v_pk_mul_f32 v[6:7], v[6:7], v[26:27] op_sel_hi:[1,0]
	v_pk_mul_f32 v[4:5], v[4:5], v[26:27] op_sel_hi:[1,0]
	s_andn2_b64 vcc, exec, s[40:41]
	v_pk_mul_f32 v[18:19], v[2:3], v[26:27] op_sel_hi:[1,0]
	v_pk_mul_f32 v[20:21], v[0:1], v[26:27] op_sel_hi:[1,0]
	s_waitcnt vmcnt(1)
	v_pk_mul_f32 v[0:1], v[8:9], v[4:5]
	v_pk_mul_f32 v[2:3], v[10:11], v[6:7]
	s_waitcnt vmcnt(0)
	v_pk_mul_f32 v[4:5], v[12:13], v[20:21]
	v_pk_mul_f32 v[6:7], v[14:15], v[18:19]
	global_store_dwordx4 v[16:17], v[0:3], off offset:512
	global_store_dwordx4 v[16:17], v[4:7], off offset:528
	s_cbranch_vccnz .LBB0_779
	s_andn2_b64 vcc, exec, s[10:11]
	s_cbranch_vccnz .LBB0_778
	s_barrier
	s_branch .LBB0_778
